# DSA attention: same no-row-maximum fast path as the differential loop (row sum <= 256 check, exact redo otherwise), per 32-key step
# baseline (speedup 1.0000x reference)
; #define LAS __attribute__((address_space(3)))
; __device__ __forceinline__ void dsa_attn_item(CParams& p, LAS unsigned char* lds, int b, int qb, int tid_in, int wave) {
;     ...
;     const int hd = wave & 3, qs = wave >> 2, r = lane & 31, hh = lane >> 5;
;     const int tb0 = b * SEQ; const int q0 = qb * 64 + 32 * qs;
;     for (int i = tid; i < 4 * 132; i += NTHREADS) bdl[i] = bd[i];
;     h16x8 qf[8];
; #pragma unroll
;     for (int s = 0; s < 8; ++s) qf[s] = *(const h16x8*)(proj + (size_t)(tb0 + q0 + r) * OD_N + 1536 + hd * 128 + 16 * s + 8 * hh);
;     f32x16 o[4];
; #pragma unroll
;     for (int d = 0; d < 4; ++d)
; #pragma unroll
;         for (int i = 0; i < 16; ++i) o[d][i] = 0.f;
;     float m_run = -INFINITY, l_run = 0.f;
;     const int qp = q0 + r;
;     const int vlo = r * 72 + ((hh ^ (r >> 3)) << 2), vhi = r * 72 + (((hh ^ (r >> 3)) ^ 2) << 2);
;     const unsigned long long* bmq = bm + (size_t)(tb0 + qp) * 64;
;     const LAS float* bdh = bdl + hd * 132;
;     const int nkt = qb + 1;
;     h16x8 pk[2], pv[2];
; #pragma unroll
;     for (int i = 0; i < 2; ++i) { const int key = i * 32 + (tid >> 4), ch = tid & 15;
;         pk[i] = *(const h16x8*)(proj + (size_t)(tb0 + key) * OD_N + 2048 + ch * 8);
;         pv[i] = *(const h16x8*)(proj + (size_t)(tb0 + key) * OD_N + 2176 + ch * 8); }
;     ATT_STAGE(0, 2048, 2176, 1);
;     unsigned long long mkn = bmq[0];
;     __syncthreads();
.LBB0_510:
	s_or_b64 exec, exec, s[4:5]
	s_mov_b32 s100, 0
	v_add_u32_e32 v145, s84, v183
	v_and_b32_e32 v80, 31, v16
	v_add_u32_e32 v0, s58, v145
	v_bfe_u32 v81, v16, 5, 1
	v_or_b32_e32 v144, v80, v0
	v_mad_i64_i32 v[2:3], s[4:5], v144, s33, v[142:143]
	v_lshlrev_b32_e32 v0, 4, v81
	v_lshl_add_u64 v[34:35], v[2:3], 0, v[0:1]
	v_or_b32_e32 v0, v80, v145
	v_add_u32_e32 v14, s58, v0
	v_ashrrev_i32_e32 v17, 4, v16
	v_lshlrev_b32_e32 v0, 3, v16
	v_add_u32_e32 v147, s58, v17
	v_and_b32_e32 v0, 0x78, v0
	v_mov_b64_e32 v[36:37], s[14:15]
	v_mad_i64_i32 v[18:19], s[4:5], v147, s33, v[36:37]
	v_lshlrev_b32_e32 v0, 1, v0
	v_add_u32_e32 v22, 32, v147
	v_lshl_add_u64 v[18:19], v[18:19], 0, v[0:1]
	v_mad_i64_i32 v[22:23], s[4:5], v22, s33, v[36:37]
	v_add_co_u32_e32 v26, vcc, s3, v18
	s_min_i32 s4, s83, 1
	s_nop 0
	v_addc_co_u32_e32 v27, vcc, 0, v19, vcc
	v_lshl_add_u64 v[22:23], v[22:23], 0, v[0:1]
	v_lshl_add_u32 v40, s4, 6, v147
	v_add_co_u32_e32 v30, vcc, s3, v22
	v_mad_i64_i32 v[32:33], s[4:5], v40, s33, v[36:37]
	s_nop 0
	v_addc_co_u32_e32 v31, vcc, 0, v23, vcc
	v_lshl_add_u64 v[32:33], v[32:33], 0, v[0:1]
	v_add_u32_e32 v40, 32, v40
	v_add_co_u32_e32 v38, vcc, s3, v32
	v_mad_i64_i32 v[36:37], s[4:5], v40, s33, v[36:37]
	v_ashrrev_i32_e32 v15, 31, v14
	v_addc_co_u32_e32 v39, vcc, 0, v33, vcc
	v_lshl_add_u64 v[36:37], v[36:37], 0, v[0:1]
	global_load_dwordx4 v[2:5], v[34:35], off offset:3104
	global_load_dwordx4 v[6:9], v[34:35], off offset:3136
	global_load_dwordx4 v[10:13], v[34:35], off offset:3168
	global_load_dwordx4 v[96:99], v[34:35], off offset:3200
	global_load_dwordx4 v[100:103], v[34:35], off offset:3232
	global_load_dwordx4 v[104:107], v[34:35], off offset:3264
	v_lshlrev_b64 v[14:15], 9, v[14:15]
	global_load_dwordx4 v[108:111], v[34:35], off offset:3296
	global_load_dwordx4 v[18:21], v[26:27], off
	global_load_dwordx4 v[22:25], v[30:31], off
	s_nop 0
	global_load_dwordx4 v[26:29], v[26:27], off offset:256
	v_add_co_u32_e32 v36, vcc, 0x1000, v36
	v_lshl_add_u64 v[14:15], s[16:17], 0, v[14:15]
	global_load_dwordx4 v[30:33], v[30:31], off offset:256
	s_nop 0
	global_load_dwordx4 v[116:119], v[38:39], off
	v_addc_co_u32_e32 v37, vcc, 0, v37, vcc
	global_load_dwordx4 v[120:123], v[38:39], off offset:256
	global_load_dwordx4 v[128:131], v[36:37], off
	global_load_dwordx4 v[112:115], v[34:35], off offset:3072
	global_load_dwordx2 v[150:151], v[14:15], off
	global_load_dwordx4 v[124:127], v[36:37], off offset:256
	v_and_b32_e32 v16, 15, v16
	v_lshlrev_b32_e32 v34, 2, v16
	v_lshlrev_b32_e32 v35, 1, v17
	v_lshl_add_u32 v153, v16, 4, 0
	v_mul_u32_u24_e32 v155, 0x480, v16
	v_and_b32_e32 v16, 6, v35
	v_bfe_u32 v36, v17, 2, 1
	v_bfe_u32 v37, v17, 3, 1
	v_and_b32_e32 v38, -13, v17
	v_lshl_or_b32 v38, v36, 3, v38
	v_lshl_or_b32 v38, v37, 2, v38
	v_and_b32_e32 v34, 0x38, v34
	v_bitop3_b32 v36, v38, v34, -4 bitop3:0x6c
	v_mul_lo_u32 v154, v17, s97
	v_add_u32_e32 v162, 0, v16
	v_lshlrev_b32_e32 v163, 1, v36
	v_add_u32_e32 v35, v153, v154
	v_add3_u32 v16, v162, v163, v155
	s_mov_b64 s[4:5], -1
	s_cmp_gt_i32 s83, -1
	v_lshlrev_b32_e32 v152, 2, v81
	s_waitcnt vmcnt(9)
	ds_write_b128 v35, v[18:21]
	s_waitcnt vmcnt(7)
	ds_write_b16 v16, v26 offset:34816
	ds_write_b16_d16_hi v16, v26 offset:34960
	ds_write_b16 v16, v27 offset:35104
	ds_write_b16_d16_hi v16, v27 offset:35248
	ds_write_b16 v16, v28 offset:35392
	ds_write_b16_d16_hi v16, v28 offset:35536
	ds_write_b16 v16, v29 offset:35680
	ds_write_b16_d16_hi v16, v29 offset:35824
	v_add_u32_e32 v16, 32, v38
	v_bitop3_b32 v16, v16, v34, -4 bitop3:0x6c
	v_lshlrev_b32_e32 v164, 1, v16
	v_add3_u32 v16, v162, v164, v155
	ds_write_b128 v35, v[22:25] offset:8704
	s_waitcnt vmcnt(6)
	ds_write_b16 v16, v30 offset:34816
	ds_write_b16_d16_hi v16, v30 offset:34960
	ds_write_b16 v16, v31 offset:35104
	ds_write_b16_d16_hi v16, v31 offset:35248
	ds_write_b16 v16, v32 offset:35392
	ds_write_b16_d16_hi v16, v32 offset:35536
	ds_write_b16 v16, v33 offset:35680
	ds_write_b16_d16_hi v16, v33 offset:35824
	s_waitcnt lgkmcnt(0)
	s_barrier
	s_cbranch_scc0 .LBB0_591
	v_lshlrev_b32_e32 v146, 2, v81
	s_movk_i32 s4, 0x100
	v_lshlrev_b32_e64 v174, v146, s4
	s_movk_i32 s4, 0x200
	v_lshlrev_b32_e64 v175, v146, s4
	s_movk_i32 s4, 0x400
	v_lshlrev_b32_e64 v176, v146, s4
	s_movk_i32 s4, 0x800
	v_lshlrev_b32_e64 v177, v146, s4
	s_mov_b32 s4, 0x10000
	v_lshlrev_b32_e64 v178, v146, s4
	s_mov_b32 s4, 0x20000
	v_lshlrev_b32_e64 v179, v146, s4
	s_mov_b32 s4, 0x40000
	v_lshlrev_b32_e64 v180, v146, s4
	s_mov_b32 s4, 0x80000
	v_lshrrev_b32_e32 v16, 3, v80
	v_lshlrev_b32_e64 v181, v146, s4
	s_mov_b32 s4, 0x1000000
	v_xor_b32_e32 v16, v81, v16
	v_lshlrev_b32_e64 v192, v146, s4
	s_brev_b32 s4, 64
	v_lshlrev_b32_e32 v17, 2, v16
	v_lshrrev_b32_e32 v168, 4, v80
	v_xor_b32_e32 v168, v81, v168
	v_lshlrev_b32_e32 v168, 4, v168
	v_lshlrev_b32_e64 v193, v146, s4
	s_brev_b32 s4, 32
	v_add_u32_e32 v16, v145, v80
	v_mov_b32_e32 v30, v1
	v_mov_b32_e32 v31, v1
	v_xor_b32_e32 v165, 8, v17
	v_lshlrev_b32_e64 v194, v146, s4
	s_brev_b32 s4, 16
	v_sub_u32_e32 v196, v16, v146
	v_mov_b32_e32 v16, v1
	v_mov_b32_e32 v17, v1
	v_mov_b32_e32 v18, v1
	v_mov_b32_e32 v19, v1
	v_mov_b32_e32 v20, v1
	v_mov_b32_e32 v21, v1
	v_mov_b32_e32 v22, v1
	v_mov_b32_e32 v23, v1
	v_mov_b32_e32 v24, v1
	v_mov_b32_e32 v25, v1
	v_mov_b32_e32 v26, v1
	v_mov_b32_e32 v27, v1
	v_mov_b32_e32 v28, v1
	v_mov_b32_e32 v29, v1
	v_mov_b64_e32 v[46:47], v[30:31]
	v_mov_b64_e32 v[62:63], v[30:31]
	v_mov_b64_e32 v[78:79], v[30:31]
	s_mov_b32 s30, 2
	v_lshl_add_u32 v166, v81, 4, 0
	v_mad_u32_u24 v167, v80, s60, 0
	v_mul_u32_u24_e32 v169, 0x110, v80
	v_lshlrev_b32_e64 v170, v146, 1
	v_lshlrev_b32_e64 v171, v146, 2
	v_lshlrev_b32_e64 v172, v146, 4
	v_lshlrev_b32_e64 v173, v146, 8
	v_lshlrev_b32_e64 v195, v146, s4
	v_mov_b32_e32 v198, 0
	v_mov_b32_e32 v201, 0xff800000
	s_movk_i32 s31, 0xbf
	v_mov_b64_e32 v[44:45], v[28:29]
	v_mov_b64_e32 v[42:43], v[26:27]
	v_mov_b64_e32 v[40:41], v[24:25]
	v_mov_b64_e32 v[38:39], v[22:23]
	v_mov_b64_e32 v[36:37], v[20:21]
	v_mov_b64_e32 v[34:35], v[18:19]
	v_mov_b64_e32 v[32:33], v[16:17]
	v_mov_b64_e32 v[60:61], v[28:29]
	v_mov_b64_e32 v[58:59], v[26:27]
	v_mov_b64_e32 v[56:57], v[24:25]
	v_mov_b64_e32 v[54:55], v[22:23]
	v_mov_b64_e32 v[52:53], v[20:21]
	v_mov_b64_e32 v[50:51], v[18:19]
	v_mov_b64_e32 v[48:49], v[16:17]
	v_mov_b64_e32 v[76:77], v[28:29]
	v_mov_b64_e32 v[74:75], v[26:27]
	v_mov_b64_e32 v[72:73], v[24:25]
	v_mov_b64_e32 v[70:71], v[22:23]
	v_mov_b64_e32 v[68:69], v[20:21]
	v_mov_b64_e32 v[66:67], v[18:19]
	v_mov_b64_e32 v[64:65], v[16:17]

; #define LAS __attribute__((address_space(3)))
; __device__ __forceinline__ f32x16 mma32(const h16x8 a, const h16x8 b, const f32x16 c) { return __builtin_amdgcn_mfma_f32_32x32x16_f16(a, b, c, 0, 0, 0); }
; __device__ __forceinline__ void dsa_attn_item(CParams& p, LAS unsigned char* lds, int b, int qb, int tid_in, int wave) {
;     ...
;     for (int kt = 0; kt < nkt; ++kt) {
;         const int k0 = kt * 64; const int cur = kt & 1;
;         const LAS h16* Ks = Ks0 + cur * 8704; const LAS h16* Vt = Vt0 + cur * 9216;
;         const unsigned long long mk = mkn; mkn = bmq[kt + 1 < nkt ? kt + 1 : kt];
;         if (kt + 1 < nkt) ATT_STAGE(cur ^ 1, 2048, 2176, kt + 2);
;         if (__ballot(mk != 0ull) != 0ull) {
;             const bool far = (k0 + 63 + 128 <= q0);
;             const float bfar = bdh[128];
; #pragma unroll
;             for (int sub = 0; sub < 2; ++sub) {
;                 const unsigned mw = (unsigned)(mk >> (32 * sub));
;                 if (__ballot(mw != 0u) == 0ull) continue;
;                 f32x16 sc;
; #pragma unroll
;                 for (int i = 0; i < 16; ++i) sc[i] = 0.f;
; #pragma unroll
;                 for (int s = 0; s < 8; ++s) sc = mma32(*(const LAS h16x8*)(Ks + (32 * sub + r) * 136 + 16 * s + 8 * hh), qf[s], sc);
;                 float mx = -INFINITY;
; #pragma unroll
;                 for (int i = 0; i < 16; ++i) { const int ko = (i & 3) + 8 * (i >> 2) + 4 * hh; const int dist = qp - (k0 + 32 * sub + ko);
;                     float bias = bfar; if (!far) bias = bdh[dist < 0 ? 0 : (dist < 128 ? dist : 128)];
.LBB0_514:
	s_waitcnt vmcnt(2)
	v_cmp_ne_u64_e32 vcc, 0, v[150:151]
	s_cbranch_vccz .LBB0_588
	s_and_b32 s4, s34, 1
	s_mul_i32 s5, s4, 0x4400
	s_mulk_i32 s4, 0x4800
	v_add3_u32 v197, v166, v169, s5
	v_add3_u32 v199, v167, v168, s4
	v_readfirstlane_b32 s6, v145
	v_cmp_ne_u32_e32 vcc, 0, v150
	s_cbranch_vccz .LdsaA_s0_skip
	s_mov_b32 s101, 0
.LdsaA_s0_top:
	ds_read_b128 v[80:83], v197 offset:0
	ds_read_b128 v[84:87], v197 offset:32
	ds_read_b128 v[88:91], v197 offset:64
	ds_read_b128 v[92:95], v197 offset:96
	ds_read_b128 v[202:205], v197 offset:128
	ds_read_b128 v[206:209], v197 offset:160
	ds_read_b128 v[210:213], v197 offset:192
	ds_read_b128 v[228:231], v197 offset:224
	ds_read_b32 v200, v184 offset:512
	s_waitcnt lgkmcnt(5)
	v_mfma_f32_32x32x16_f16 v[236:251], v[80:83], v[112:115], 0
	v_mfma_f32_32x32x16_f16 v[236:251], v[84:87], v[2:5], v[236:251]
	v_mfma_f32_32x32x16_f16 v[236:251], v[88:91], v[6:9], v[236:251]
	v_mfma_f32_32x32x16_f16 v[236:251], v[92:95], v[10:13], v[236:251]
	s_waitcnt lgkmcnt(1)
	v_mfma_f32_32x32x16_f16 v[236:251], v[202:205], v[96:99], v[236:251]
	v_mfma_f32_32x32x16_f16 v[236:251], v[206:209], v[100:103], v[236:251]
	v_mfma_f32_32x32x16_f16 v[236:251], v[210:213], v[104:107], v[236:251]
	v_mfma_f32_32x32x16_f16 v[236:251], v[228:231], v[108:111], v[236:251]
	v_lshrrev_b32_e32 v214, v146, v150
	s_cmp_le_i32 s31, s6
	s_cbranch_scc1 .LdsaA_s0_far
	v_subrev_u32_e32 v202, 0, v196
	v_med3_i32 v202, v202, 0, v226
	v_lshl_add_u32 v202, v202, 2, v184
	ds_read_b32 v202, v202
	v_subrev_u32_e32 v203, 1, v196
	v_med3_i32 v203, v203, 0, v226
	v_lshl_add_u32 v203, v203, 2, v184
	ds_read_b32 v203, v203
	v_subrev_u32_e32 v204, 2, v196
	v_med3_i32 v204, v204, 0, v226
	v_lshl_add_u32 v204, v204, 2, v184
	ds_read_b32 v204, v204
	v_subrev_u32_e32 v205, 3, v196
	v_med3_i32 v205, v205, 0, v226
	v_lshl_add_u32 v205, v205, 2, v184
	ds_read_b32 v205, v205
	v_subrev_u32_e32 v206, 8, v196
	v_med3_i32 v206, v206, 0, v226
	v_lshl_add_u32 v206, v206, 2, v184
	ds_read_b32 v206, v206
	v_subrev_u32_e32 v207, 9, v196
	v_med3_i32 v207, v207, 0, v226
	v_lshl_add_u32 v207, v207, 2, v184
	ds_read_b32 v207, v207
	v_subrev_u32_e32 v208, 10, v196
	v_med3_i32 v208, v208, 0, v226
	v_lshl_add_u32 v208, v208, 2, v184
	ds_read_b32 v208, v208
	v_subrev_u32_e32 v209, 11, v196
	v_med3_i32 v209, v209, 0, v226
	v_lshl_add_u32 v209, v209, 2, v184
	ds_read_b32 v209, v209
	v_subrev_u32_e32 v210, 16, v196
	v_med3_i32 v210, v210, 0, v226
	v_lshl_add_u32 v210, v210, 2, v184
	ds_read_b32 v210, v210
	v_subrev_u32_e32 v211, 17, v196
	v_med3_i32 v211, v211, 0, v226
	v_lshl_add_u32 v211, v211, 2, v184
	ds_read_b32 v211, v211
	v_subrev_u32_e32 v212, 18, v196
	v_med3_i32 v212, v212, 0, v226
	v_lshl_add_u32 v212, v212, 2, v184
	ds_read_b32 v212, v212
	v_subrev_u32_e32 v213, 19, v196
	v_med3_i32 v213, v213, 0, v226
	v_lshl_add_u32 v213, v213, 2, v184
	ds_read_b32 v213, v213
	v_subrev_u32_e32 v80, 24, v196
	v_med3_i32 v80, v80, 0, v226
	v_lshl_add_u32 v80, v80, 2, v184
	ds_read_b32 v80, v80
	v_subrev_u32_e32 v81, 25, v196
	v_med3_i32 v81, v81, 0, v226
	v_lshl_add_u32 v81, v81, 2, v184
	ds_read_b32 v81, v81
	v_subrev_u32_e32 v82, 26, v196
	v_med3_i32 v82, v82, 0, v226
	v_lshl_add_u32 v82, v82, 2, v184
	ds_read_b32 v82, v82
	v_subrev_u32_e32 v83, 27, v196
	v_med3_i32 v83, v83, 0, v226
	v_lshl_add_u32 v83, v83, 2, v184
	ds_read_b32 v83, v83
	s_waitcnt lgkmcnt(0)
	s_nop 2
	v_add_f32_e32 v236, v236, v202
	v_add_f32_e32 v237, v237, v203
	v_add_f32_e32 v238, v238, v204
	v_add_f32_e32 v239, v239, v205
	v_add_f32_e32 v240, v240, v206
	v_add_f32_e32 v241, v241, v207
	v_add_f32_e32 v242, v242, v208
	v_add_f32_e32 v243, v243, v209
	v_add_f32_e32 v244, v244, v210
	v_add_f32_e32 v245, v245, v211
	v_add_f32_e32 v246, v246, v212
	v_add_f32_e32 v247, v247, v213
	v_add_f32_e32 v248, v248, v80
	v_add_f32_e32 v249, v249, v81
	v_add_f32_e32 v250, v250, v82
	v_add_f32_e32 v251, v251, v83
	v_mov_b32_e32 v200, 0
	s_branch .LdsaA_s0_msk

; #define LAS __attribute__((address_space(3)))
; __device__ __forceinline__ f32x16 mma32(const h16x8 a, const h16x8 b, const f32x16 c) { return __builtin_amdgcn_mfma_f32_32x32x16_f16(a, b, c, 0, 0, 0); }
; __device__ __forceinline__ void dsa_attn_item(CParams& p, LAS unsigned char* lds, int b, int qb, int tid_in, int wave) {
;     ...
;                 float mx = -INFINITY;
; #pragma unroll
;                 for (int i = 0; i < 16; ++i) { const int ko = (i & 3) + 8 * (i >> 2) + 4 * hh; const int dist = qp - (k0 + 32 * sub + ko);
;                     float bias = bfar; if (!far) bias = bdh[dist < 0 ? 0 : (dist < 128 ? dist : 128)];
;                     const float v = ((mw >> ko) & 1u) ? sc[i] + bias : -INFINITY; sc[i] = v; mx = fmaxf(mx, v); }
;                 mx = fmaxf(mx, __shfl_xor(mx, 32));
;                 const float m_new = fmaxf(m_run, mx);
;                 const float msafe = (m_new == -INFINITY) ? 0.f : m_new;
;                 const float alpha = __builtin_amdgcn_exp2f(m_run - msafe);
;                 const bool resc = __ballot(m_new > m_run) != 0ull;
;                 float ls = 0.f;
; #pragma unroll
;                 for (int i = 0; i < 16; ++i) { const float e = __builtin_amdgcn_exp2f(sc[i] - msafe); sc[i] = e; ls += e; }
;                 ls += __shfl_xor(ls, 32);
;                 l_run = l_run * alpha + ls; m_run = m_new;
;                 if (resc) {
; #pragma unroll
;                     for (int d = 0; d < 4; ++d)
; #pragma unroll
;                         for (int i = 0; i < 16; ++i) o[d][i] *= alpha;
;                 }
; #pragma unroll
;                 for (int s2 = 0; s2 < 2; ++s2) {
;                     h16x8 pf;
; #pragma unroll
;                     for (int jj = 0; jj < 8; ++jj) pf[jj] = (h16)sc[8 * s2 + jj];
; #pragma unroll
;                     for (int d = 0; d < 4; ++d) {
;                         const int coff = 32 * d * 72 + ((((sub << 1) | s2) ^ d) << 4);
;                         const h16x4 lo = *(const LAS h16x4*)(Vt + vlo + coff), hi = *(const LAS h16x4*)(Vt + vhi + coff);
;                         h16x8 vf; vf[0] = lo[0]; vf[1] = lo[1]; vf[2] = lo[2]; vf[3] = lo[3]; vf[4] = hi[0]; vf[5] = hi[1]; vf[6] = hi[2]; vf[7] = hi[3];
;                         o[d] = mma32(vf, pf, o[d]);
;                     }
.LdsaA_s0_msk:
	v_bfe_i32 v80, v214, 0, 1
	v_bfi_b32 v236, v80, v236, v225
	v_bfe_i32 v81, v214, 1, 1
	v_bfi_b32 v237, v81, v237, v225
	v_bfe_i32 v82, v214, 2, 1
	v_bfi_b32 v238, v82, v238, v225
	v_bfe_i32 v83, v214, 3, 1
	v_bfi_b32 v239, v83, v239, v225
	v_bfe_i32 v80, v214, 8, 1
	v_bfi_b32 v240, v80, v240, v225
	v_bfe_i32 v81, v214, 9, 1
	v_bfi_b32 v241, v81, v241, v225
	v_bfe_i32 v82, v214, 10, 1
	v_bfi_b32 v242, v82, v242, v225
	v_bfe_i32 v83, v214, 11, 1
	v_bfi_b32 v243, v83, v243, v225
	v_bfe_i32 v80, v214, 16, 1
	v_bfi_b32 v244, v80, v244, v225
	v_bfe_i32 v81, v214, 17, 1
	v_bfi_b32 v245, v81, v245, v225
	v_bfe_i32 v82, v214, 18, 1
	v_bfi_b32 v246, v82, v246, v225
	v_bfe_i32 v83, v214, 19, 1
	v_bfi_b32 v247, v83, v247, v225
	v_bfe_i32 v80, v214, 24, 1
	v_bfi_b32 v248, v80, v248, v225
	v_bfe_i32 v81, v214, 25, 1
	v_bfi_b32 v249, v81, v249, v225
	v_bfe_i32 v82, v214, 26, 1
	v_bfi_b32 v250, v82, v250, v225
	v_bfe_i32 v83, v214, 27, 1
	v_bfi_b32 v251, v83, v251, v225
	s_cmp_eq_u32 s100, 0
	s_cbranch_scc1 .LdsaA_s0_slow
	s_waitcnt lgkmcnt(0)
	v_sub_f32_e32 v90, v201, v200
.LdsaA_s0_t2:
	v_pk_add_f32 v[236:237], v[236:237], v[90:91] op_sel_hi:[1,0] neg_lo:[0,1] neg_hi:[0,1]
	v_pk_add_f32 v[238:239], v[238:239], v[90:91] op_sel_hi:[1,0] neg_lo:[0,1] neg_hi:[0,1]
	v_pk_add_f32 v[240:241], v[240:241], v[90:91] op_sel_hi:[1,0] neg_lo:[0,1] neg_hi:[0,1]
	v_pk_add_f32 v[242:243], v[242:243], v[90:91] op_sel_hi:[1,0] neg_lo:[0,1] neg_hi:[0,1]
	v_pk_add_f32 v[244:245], v[244:245], v[90:91] op_sel_hi:[1,0] neg_lo:[0,1] neg_hi:[0,1]
	v_pk_add_f32 v[246:247], v[246:247], v[90:91] op_sel_hi:[1,0] neg_lo:[0,1] neg_hi:[0,1]
	v_pk_add_f32 v[248:249], v[248:249], v[90:91] op_sel_hi:[1,0] neg_lo:[0,1] neg_hi:[0,1]
	v_pk_add_f32 v[250:251], v[250:251], v[90:91] op_sel_hi:[1,0] neg_lo:[0,1] neg_hi:[0,1]
	v_exp_f32_e32 v236, v236
	v_exp_f32_e32 v237, v237
	v_exp_f32_e32 v238, v238
	v_exp_f32_e32 v239, v239
	v_exp_f32_e32 v240, v240
	v_exp_f32_e32 v241, v241
	v_exp_f32_e32 v242, v242
	v_exp_f32_e32 v243, v243
	v_exp_f32_e32 v244, v244
	v_exp_f32_e32 v245, v245
	v_exp_f32_e32 v246, v246
	v_exp_f32_e32 v247, v247
	v_exp_f32_e32 v248, v248
	v_exp_f32_e32 v249, v249
	v_exp_f32_e32 v250, v250
	v_exp_f32_e32 v251, v251
	v_pk_add_f32 v[92:93], v[236:237], v[238:239]
	v_pk_add_f32 v[92:93], v[92:93], v[240:241]
	v_pk_add_f32 v[92:93], v[92:93], v[242:243]
	v_pk_add_f32 v[92:93], v[92:93], v[244:245]
	v_pk_add_f32 v[92:93], v[92:93], v[246:247]
	v_pk_add_f32 v[92:93], v[92:93], v[248:249]
	v_pk_add_f32 v[92:93], v[92:93], v[250:251]
	s_nop 0
	v_add_f32_e32 v92, v92, v93
	ds_bpermute_b32 v215, v185, v92
	v_cvt_pk_f16_f32 v232, v236, v237
	v_cvt_pk_f16_f32 v233, v238, v239
	v_cvt_pk_f16_f32 v234, v240, v241
	v_cvt_pk_f16_f32 v235, v242, v243
	v_cvt_pk_f16_f32 v228, v244, v245
	v_cvt_pk_f16_f32 v229, v246, v247
	v_cvt_pk_f16_f32 v230, v248, v249
	v_cvt_pk_f16_f32 v231, v250, v251
	s_waitcnt lgkmcnt(0)
	v_add_f32_e32 v92, v92, v215
	s_cmp_lg_u32 s101, 0
	s_cbranch_scc1 .LdsaA_s0_ok
	v_cmp_nge_f32_e32 vcc, 0x43800000, v92
	s_cbranch_vccz .LdsaA_s0_ok
	s_mov_b32 s100, 0
	s_mov_b32 s101, 1
	s_branch .LdsaA_s0_top
.LdsaA_s0_ok:
	v_add_f32_e32 v198, v198, v92
	ds_read_b128 v[236:239], v199 offset:34848
	ds_read_b128 v[240:243], v199 offset:39424
	ds_read_b128 v[244:247], v199 offset:44128
	ds_read_b128 v[248:251], v199 offset:48704
	ds_read_b128 v[80:83], v199 offset:34816
	ds_read_b128 v[84:87], v199 offset:39456
	ds_read_b128 v[88:91], v199 offset:44096
	ds_read_b128 v[92:95], v199 offset:48736
	s_waitcnt lgkmcnt(4)
	v_mfma_f32_32x32x16_f16 v[64:79], v[236:239], v[228:231], v[64:79]
	v_mfma_f32_32x32x16_f16 v[48:63], v[240:243], v[228:231], v[48:63]
	v_mfma_f32_32x32x16_f16 v[32:47], v[244:247], v[228:231], v[32:47]
	v_mfma_f32_32x32x16_f16 v[16:31], v[248:251], v[228:231], v[16:31]
	s_waitcnt lgkmcnt(0)
	v_mfma_f32_32x32x16_f16 v[64:79], v[80:83], v[232:235], v[64:79]
	v_mfma_f32_32x32x16_f16 v[48:63], v[84:87], v[232:235], v[48:63]
	v_mfma_f32_32x32x16_f16 v[32:47], v[88:91], v[232:235], v[32:47]
	v_mfma_f32_32x32x16_f16 v[16:31], v[92:95], v[232:235], v[16:31]
; #define LAS __attribute__((address_space(3)))
; __device__ __forceinline__ f32x16 mma32(const h16x8 a, const h16x8 b, const f32x16 c) { return __builtin_amdgcn_mfma_f32_32x32x16_f16(a, b, c, 0, 0, 0); }
; __device__ __forceinline__ void dsa_attn_item(CParams& p, LAS unsigned char* lds, int b, int qb, int tid_in, int wave) {
;     ...
; #pragma unroll
;             for (int sub = 0; sub < 2; ++sub) {
;                 const unsigned mw = (unsigned)(mk >> (32 * sub));
;                 if (__ballot(mw != 0u) == 0ull) continue;
;                 f32x16 sc;
; #pragma unroll
;                 for (int i = 0; i < 16; ++i) sc[i] = 0.f;
; #pragma unroll
;                 for (int s = 0; s < 8; ++s) sc = mma32(*(const LAS h16x8*)(Ks + (32 * sub + r) * 136 + 16 * s + 8 * hh), qf[s], sc);
;                 float mx = -INFINITY;
; #pragma unroll
;                 for (int i = 0; i < 16; ++i) { const int ko = (i & 3) + 8 * (i >> 2) + 4 * hh; const int dist = qp - (k0 + 32 * sub + ko);
;                     float bias = bfar; if (!far) bias = bdh[dist < 0 ? 0 : (dist < 128 ? dist : 128)];
.LdsaA_s0_skip:
	v_cmp_ne_u32_e32 vcc, 0, v151
	s_cbranch_vccz .LdsaA_s1_skip
	s_mov_b32 s101, 0
.LdsaA_s1_top:
	ds_read_b128 v[80:83], v197 offset:8704
	ds_read_b128 v[84:87], v197 offset:8736
	ds_read_b128 v[88:91], v197 offset:8768
	ds_read_b128 v[92:95], v197 offset:8800
	ds_read_b128 v[202:205], v197 offset:8832
	ds_read_b128 v[206:209], v197 offset:8864
	ds_read_b128 v[210:213], v197 offset:8896
	ds_read_b128 v[228:231], v197 offset:8928
	ds_read_b32 v200, v184 offset:512
	s_waitcnt lgkmcnt(5)
	v_mfma_f32_32x32x16_f16 v[236:251], v[80:83], v[112:115], 0
	v_mfma_f32_32x32x16_f16 v[236:251], v[84:87], v[2:5], v[236:251]
	v_mfma_f32_32x32x16_f16 v[236:251], v[88:91], v[6:9], v[236:251]
	v_mfma_f32_32x32x16_f16 v[236:251], v[92:95], v[10:13], v[236:251]
	s_waitcnt lgkmcnt(1)
	v_mfma_f32_32x32x16_f16 v[236:251], v[202:205], v[96:99], v[236:251]
	v_mfma_f32_32x32x16_f16 v[236:251], v[206:209], v[100:103], v[236:251]
	v_mfma_f32_32x32x16_f16 v[236:251], v[210:213], v[104:107], v[236:251]
	v_mfma_f32_32x32x16_f16 v[236:251], v[228:231], v[108:111], v[236:251]
	v_lshrrev_b32_e32 v214, v146, v151
	s_cmp_le_i32 s31, s6
	s_cbranch_scc1 .LdsaA_s1_far
	v_subrev_u32_e32 v202, 32, v196
	v_med3_i32 v202, v202, 0, v226
	v_lshl_add_u32 v202, v202, 2, v184
	ds_read_b32 v202, v202
	v_subrev_u32_e32 v203, 33, v196
	v_med3_i32 v203, v203, 0, v226
	v_lshl_add_u32 v203, v203, 2, v184
	ds_read_b32 v203, v203
	v_subrev_u32_e32 v204, 34, v196
	v_med3_i32 v204, v204, 0, v226
	v_lshl_add_u32 v204, v204, 2, v184
	ds_read_b32 v204, v204
	v_subrev_u32_e32 v205, 35, v196
	v_med3_i32 v205, v205, 0, v226
	v_lshl_add_u32 v205, v205, 2, v184
	ds_read_b32 v205, v205
	v_subrev_u32_e32 v206, 40, v196
	v_med3_i32 v206, v206, 0, v226
	v_lshl_add_u32 v206, v206, 2, v184
	ds_read_b32 v206, v206
	v_subrev_u32_e32 v207, 41, v196
	v_med3_i32 v207, v207, 0, v226
	v_lshl_add_u32 v207, v207, 2, v184
	ds_read_b32 v207, v207
	v_subrev_u32_e32 v208, 42, v196
	v_med3_i32 v208, v208, 0, v226
	v_lshl_add_u32 v208, v208, 2, v184
	ds_read_b32 v208, v208
	v_subrev_u32_e32 v209, 43, v196
	v_med3_i32 v209, v209, 0, v226
	v_lshl_add_u32 v209, v209, 2, v184
	ds_read_b32 v209, v209
	v_subrev_u32_e32 v210, 48, v196
	v_med3_i32 v210, v210, 0, v226
	v_lshl_add_u32 v210, v210, 2, v184
	ds_read_b32 v210, v210
	v_subrev_u32_e32 v211, 49, v196
	v_med3_i32 v211, v211, 0, v226
	v_lshl_add_u32 v211, v211, 2, v184
	ds_read_b32 v211, v211
	v_subrev_u32_e32 v212, 50, v196
	v_med3_i32 v212, v212, 0, v226
	v_lshl_add_u32 v212, v212, 2, v184
	ds_read_b32 v212, v212
	v_subrev_u32_e32 v213, 51, v196
	v_med3_i32 v213, v213, 0, v226
	v_lshl_add_u32 v213, v213, 2, v184
	ds_read_b32 v213, v213
	v_subrev_u32_e32 v80, 56, v196
	v_med3_i32 v80, v80, 0, v226
	v_lshl_add_u32 v80, v80, 2, v184
	ds_read_b32 v80, v80
	v_subrev_u32_e32 v81, 57, v196
	v_med3_i32 v81, v81, 0, v226
	v_lshl_add_u32 v81, v81, 2, v184
	ds_read_b32 v81, v81
	v_subrev_u32_e32 v82, 58, v196
	v_med3_i32 v82, v82, 0, v226
	v_lshl_add_u32 v82, v82, 2, v184
	ds_read_b32 v82, v82
	v_subrev_u32_e32 v83, 59, v196
	v_med3_i32 v83, v83, 0, v226
	v_lshl_add_u32 v83, v83, 2, v184
	ds_read_b32 v83, v83
	s_waitcnt lgkmcnt(0)
	s_nop 2
	v_add_f32_e32 v236, v236, v202
	v_add_f32_e32 v237, v237, v203
	v_add_f32_e32 v238, v238, v204
	v_add_f32_e32 v239, v239, v205
	v_add_f32_e32 v240, v240, v206
	v_add_f32_e32 v241, v241, v207
	v_add_f32_e32 v242, v242, v208
	v_add_f32_e32 v243, v243, v209
	v_add_f32_e32 v244, v244, v210
	v_add_f32_e32 v245, v245, v211
	v_add_f32_e32 v246, v246, v212
	v_add_f32_e32 v247, v247, v213
	v_add_f32_e32 v248, v248, v80
	v_add_f32_e32 v249, v249, v81
	v_add_f32_e32 v250, v250, v82
	v_add_f32_e32 v251, v251, v83
	v_mov_b32_e32 v200, 0
	s_branch .LdsaA_s1_msk

; #define LAS __attribute__((address_space(3)))
; __device__ __forceinline__ f32x16 mma32(const h16x8 a, const h16x8 b, const f32x16 c) { return __builtin_amdgcn_mfma_f32_32x32x16_f16(a, b, c, 0, 0, 0); }
; __device__ __forceinline__ void dsa_attn_item(CParams& p, LAS unsigned char* lds, int b, int qb, int tid_in, int wave) {
;     ...
;                 ls += __shfl_xor(ls, 32);
;                 l_run = l_run * alpha + ls; m_run = m_new;
;                 if (resc) {
; #pragma unroll
;                     for (int d = 0; d < 4; ++d)
; #pragma unroll
;                         for (int i = 0; i < 16; ++i) o[d][i] *= alpha;
;                 }
; #pragma unroll
;                 for (int s2 = 0; s2 < 2; ++s2) {
;                     h16x8 pf;
; #pragma unroll
;                     for (int jj = 0; jj < 8; ++jj) pf[jj] = (h16)sc[8 * s2 + jj];
; #pragma unroll
;                     for (int d = 0; d < 4; ++d) {
;                         const int coff = 32 * d * 72 + ((((sub << 1) | s2) ^ d) << 4);
;                         const h16x4 lo = *(const LAS h16x4*)(Vt + vlo + coff), hi = *(const LAS h16x4*)(Vt + vhi + coff);
;                         h16x8 vf; vf[0] = lo[0]; vf[1] = lo[1]; vf[2] = lo[2]; vf[3] = lo[3]; vf[4] = hi[0]; vf[5] = hi[1]; vf[6] = hi[2]; vf[7] = hi[3];
;                         o[d] = mma32(vf, pf, o[d]);
;                     }
.LdsaA_s1_ok:
	v_add_f32_e32 v198, v198, v92
	ds_read_b128 v[236:239], v199 offset:34912
	ds_read_b128 v[240:243], v199 offset:39488
	ds_read_b128 v[244:247], v199 offset:44064
	ds_read_b128 v[248:251], v199 offset:48640
	ds_read_b128 v[80:83], v199 offset:34880
	ds_read_b128 v[84:87], v199 offset:39520
	ds_read_b128 v[88:91], v199 offset:44032
	ds_read_b128 v[92:95], v199 offset:48672
	s_waitcnt lgkmcnt(4)
	v_mfma_f32_32x32x16_f16 v[64:79], v[236:239], v[228:231], v[64:79]
	v_mfma_f32_32x32x16_f16 v[48:63], v[240:243], v[228:231], v[48:63]
	v_mfma_f32_32x32x16_f16 v[32:47], v[244:247], v[228:231], v[32:47]
	v_mfma_f32_32x32x16_f16 v[16:31], v[248:251], v[228:231], v[16:31]
	s_waitcnt lgkmcnt(0)
	v_mfma_f32_32x32x16_f16 v[64:79], v[80:83], v[232:235], v[64:79]
	v_mfma_f32_32x32x16_f16 v[48:63], v[84:87], v[232:235], v[48:63]
	v_mfma_f32_32x32x16_f16 v[32:47], v[88:91], v[232:235], v[32:47]
	v_mfma_f32_32x32x16_f16 v[16:31], v[92:95], v[232:235], v[16:31]

; __device__ __forceinline__ void dsa_attn_item(CParams& p, LAS unsigned char* lds, int b, int qb, int tid_in, int wave) {
;     ...
;                 float mx = -INFINITY;
; #pragma unroll
;                 for (int i = 0; i < 16; ++i) { const int ko = (i & 3) + 8 * (i >> 2) + 4 * hh; const int dist = qp - (k0 + 32 * sub + ko);
;                     float bias = bfar; if (!far) bias = bdh[dist < 0 ? 0 : (dist < 128 ? dist : 128)];
;                     const float v = ((mw >> ko) & 1u) ? sc[i] + bias : -INFINITY; sc[i] = v; mx = fmaxf(mx, v); }
;                 mx = fmaxf(mx, __shfl_xor(mx, 32));
;                 const float m_new = fmaxf(m_run, mx);
;                 const float msafe = (m_new == -INFINITY) ? 0.f : m_new;
;                 const float alpha = __builtin_amdgcn_exp2f(m_run - msafe);
;                 const bool resc = __ballot(m_new > m_run) != 0ull;
;                 float ls = 0.f;
; #pragma unroll
;                 for (int i = 0; i < 16; ++i) { const float e = __builtin_amdgcn_exp2f(sc[i] - msafe); sc[i] = e; ls += e; }
;                 ls += __shfl_xor(ls, 32);
;                 l_run = l_run * alpha + ls; m_run = m_new;
;                 if (resc) {
; #pragma unroll
;                     for (int d = 0; d < 4; ++d)
; #pragma unroll
;                         for (int i = 0; i < 16; ++i) o[d][i] *= alpha;
;                 }
.LdsaA_s0_slow:
	v_max3_f32 v84, v236, v237, v238
	v_max3_f32 v84, v84, v239, v240
	v_max3_f32 v84, v84, v241, v242
	v_max3_f32 v84, v84, v243, v244
	v_max3_f32 v84, v84, v245, v246
	v_max3_f32 v84, v84, v247, v248
	v_max3_f32 v84, v84, v249, v250
	v_max_f32_e32 v84, v84, v251
	s_waitcnt lgkmcnt(0)
	v_add_f32_e32 v84, v84, v200
	ds_bpermute_b32 v215, v185, v84
	s_waitcnt lgkmcnt(0)
	v_max3_f32 v85, v201, v84, v215
	v_cmp_neq_f32_e32 vcc, s78, v85
	s_nop 1
	v_cndmask_b32_e32 v86, 0, v85, vcc
	v_sub_f32_e32 v88, v201, v86
	v_exp_f32_e32 v88, v88
	v_cmp_gt_f32_e32 vcc, v85, v201
	v_sub_f32_e32 v90, v86, v200
	v_mov_b32_e32 v201, v85
	v_mul_f32_e32 v198, v198, v88
	s_cbranch_vccz .LdsaA_s0_nomove
	v_pk_mul_f32 v[64:65], v[64:65], v[88:89] op_sel_hi:[1,0]
	v_pk_mul_f32 v[66:67], v[66:67], v[88:89] op_sel_hi:[1,0]
	v_pk_mul_f32 v[68:69], v[68:69], v[88:89] op_sel_hi:[1,0]
	v_pk_mul_f32 v[70:71], v[70:71], v[88:89] op_sel_hi:[1,0]
	v_pk_mul_f32 v[72:73], v[72:73], v[88:89] op_sel_hi:[1,0]
	v_pk_mul_f32 v[74:75], v[74:75], v[88:89] op_sel_hi:[1,0]
	v_pk_mul_f32 v[76:77], v[76:77], v[88:89] op_sel_hi:[1,0]
	v_pk_mul_f32 v[78:79], v[78:79], v[88:89] op_sel_hi:[1,0]
	v_pk_mul_f32 v[48:49], v[48:49], v[88:89] op_sel_hi:[1,0]
	v_pk_mul_f32 v[50:51], v[50:51], v[88:89] op_sel_hi:[1,0]
	v_pk_mul_f32 v[52:53], v[52:53], v[88:89] op_sel_hi:[1,0]
	v_pk_mul_f32 v[54:55], v[54:55], v[88:89] op_sel_hi:[1,0]
	v_pk_mul_f32 v[56:57], v[56:57], v[88:89] op_sel_hi:[1,0]
	v_pk_mul_f32 v[58:59], v[58:59], v[88:89] op_sel_hi:[1,0]
	v_pk_mul_f32 v[60:61], v[60:61], v[88:89] op_sel_hi:[1,0]
	v_pk_mul_f32 v[62:63], v[62:63], v[88:89] op_sel_hi:[1,0]
	v_pk_mul_f32 v[32:33], v[32:33], v[88:89] op_sel_hi:[1,0]
	v_pk_mul_f32 v[34:35], v[34:35], v[88:89] op_sel_hi:[1,0]
	v_pk_mul_f32 v[36:37], v[36:37], v[88:89] op_sel_hi:[1,0]
	v_pk_mul_f32 v[38:39], v[38:39], v[88:89] op_sel_hi:[1,0]
	v_pk_mul_f32 v[40:41], v[40:41], v[88:89] op_sel_hi:[1,0]
	v_pk_mul_f32 v[42:43], v[42:43], v[88:89] op_sel_hi:[1,0]
	v_pk_mul_f32 v[44:45], v[44:45], v[88:89] op_sel_hi:[1,0]
	v_pk_mul_f32 v[46:47], v[46:47], v[88:89] op_sel_hi:[1,0]
	v_pk_mul_f32 v[16:17], v[16:17], v[88:89] op_sel_hi:[1,0]
	v_pk_mul_f32 v[18:19], v[18:19], v[88:89] op_sel_hi:[1,0]
	v_pk_mul_f32 v[20:21], v[20:21], v[88:89] op_sel_hi:[1,0]
	v_pk_mul_f32 v[22:23], v[22:23], v[88:89] op_sel_hi:[1,0]
	v_pk_mul_f32 v[24:25], v[24:25], v[88:89] op_sel_hi:[1,0]
	v_pk_mul_f32 v[26:27], v[26:27], v[88:89] op_sel_hi:[1,0]
	v_pk_mul_f32 v[28:29], v[28:29], v[88:89] op_sel_hi:[1,0]
	v_pk_mul_f32 v[30:31], v[30:31], v[88:89] op_sel_hi:[1,0]
.LdsaA_s0_nomove:
	v_cmp_neq_f32_e32 vcc, s78, v201
	s_cmp_eq_u64 vcc, exec
	s_cselect_b32 s100, 1, 0
	s_branch .LdsaA_s0_t2
